# GDN: wave 0 computes the next block's beta / log-decay chain at the end of the current block (after all recurrence waves finished the last group) instead of at the block head where seven waves waited
# baseline (speedup 1.0000x reference)
.LBB0_537:
	v_mov_b32_e32 v112, v1
	s_waitcnt vmcnt(6)
	v_lshlrev_b32_e32 v24, 16, v2
	v_lshlrev_b32_e32 v38, 3, v112
	v_and_b32_e32 v23, 0x78, v38
	v_lshl_add_u32 v32, v23, 2, 0
	v_ashrrev_i32_e32 v22, 4, v112
	v_and_b32_e32 v25, 0xffff0000, v2
	v_lshlrev_b32_e32 v26, 16, v3
	v_and_b32_e32 v27, 0xffff0000, v3
	v_lshlrev_b32_e32 v28, 16, v4
	v_and_b32_e32 v29, 0xffff0000, v4
	v_lshlrev_b32_e32 v30, 16, v5
	v_and_b32_e32 v31, 0xffff0000, v5
	v_pk_mul_f32 v[26:27], v[26:27], s[74:75] op_sel_hi:[1,0]
	v_pk_mul_f32 v[24:25], v[24:25], s[74:75] op_sel_hi:[1,0]
	v_mad_u64_u32 v[34:35], s[0:1], v22, s84, v[32:33]
	ds_write_b128 v34, v[24:27]
	v_pk_mul_f32 v[26:27], v[30:31], s[74:75] op_sel_hi:[1,0]
	v_pk_mul_f32 v[24:25], v[28:29], s[74:75] op_sel_hi:[1,0]
	ds_write_b128 v34, v[24:27] offset:16
	s_waitcnt vmcnt(5)
	v_lshlrev_b32_e32 v24, 16, v6
	v_and_b32_e32 v25, 0xffff0000, v6
	v_lshlrev_b32_e32 v26, 16, v7
	v_and_b32_e32 v27, 0xffff0000, v7
	v_lshlrev_b32_e32 v28, 16, v8
	v_and_b32_e32 v29, 0xffff0000, v8
	v_add_u32_e32 v113, 0x200, v112
	v_lshlrev_b32_e32 v30, 16, v9
	v_and_b32_e32 v31, 0xffff0000, v9
	ds_write_b128 v34, v[24:27] offset:33792
	ds_write_b128 v34, v[28:31] offset:33808
	v_ashrrev_i32_e32 v24, 4, v113
	s_waitcnt vmcnt(4)
	v_lshlrev_b32_e32 v26, 16, v10
	v_and_b32_e32 v27, 0xffff0000, v10
	v_lshlrev_b32_e32 v28, 16, v11
	v_and_b32_e32 v29, 0xffff0000, v11
	v_lshlrev_b32_e32 v30, 16, v12
	v_and_b32_e32 v31, 0xffff0000, v12
	v_lshlrev_b32_e32 v34, 16, v13
	v_and_b32_e32 v35, 0xffff0000, v13
	v_pk_mul_f32 v[28:29], v[28:29], s[74:75] op_sel_hi:[1,0]
	v_pk_mul_f32 v[26:27], v[26:27], s[74:75] op_sel_hi:[1,0]
	v_mad_u64_u32 v[36:37], s[0:1], v24, s84, v[32:33]
	ds_write_b128 v36, v[26:29]
	v_pk_mul_f32 v[28:29], v[34:35], s[74:75] op_sel_hi:[1,0]
	v_pk_mul_f32 v[26:27], v[30:31], s[74:75] op_sel_hi:[1,0]
	ds_write_b128 v36, v[26:29] offset:16
	s_waitcnt vmcnt(3)
	v_lshlrev_b32_e32 v26, 16, v14
	v_and_b32_e32 v27, 0xffff0000, v14
	v_lshlrev_b32_e32 v28, 16, v15
	v_and_b32_e32 v29, 0xffff0000, v15
	v_lshlrev_b32_e32 v30, 16, v16
	v_and_b32_e32 v31, 0xffff0000, v16
	v_lshlrev_b32_e32 v32, 16, v17
	v_and_b32_e32 v33, 0xffff0000, v17
	ds_write_b128 v36, v[26:29] offset:33792
	ds_write_b128 v36, v[30:33] offset:33808
	v_ashrrev_i32_e32 v26, 3, v112
	v_and_b32_e32 v28, 56, v38
	v_lshlrev_b32_e32 v25, 8, v26
	v_lshlrev_b32_e32 v27, 2, v28
	s_waitcnt vmcnt(2)
	v_lshlrev_b32_e32 v30, 16, v18
	v_and_b32_e32 v31, 0xffff0000, v18
	v_lshlrev_b32_e32 v32, 16, v19
	v_and_b32_e32 v33, 0xffff0000, v19
	v_add3_u32 v25, s85, v25, v27
	v_cmp_gt_i32_e32 vcc, 64, v112
	v_and_b32_e32 v95, 3, v112
	v_lshlrev_b32_e32 v34, 16, v20
	v_and_b32_e32 v35, 0xffff0000, v20
	v_lshlrev_b32_e32 v36, 16, v21
	v_and_b32_e32 v37, 0xffff0000, v21
	ds_write_b128 v25, v[30:33]
	ds_write_b128 v25, v[34:37] offset:16
	s_cmp_eq_u32 s17, 0
	s_cselect_b64 s[4:5], -1, 0
	s_and_b64 vcc, vcc, s[4:5]
	s_and_saveexec_b64 s[0:1], vcc
	s_cbranch_execz .LBB0_539
	s_waitcnt vmcnt(0)
	v_add_f32_e32 v25, v124, v127
	s_mov_b32 s3, 0xbfb8aa3b
	v_mul_f32_e64 v27, |v25|, s3
	v_exp_f32_e32 v27, v27
	s_mov_b32 s3, 0x3f2aaaab
	v_max_f32_e32 v25, 0, v25
	v_mul_f32_e32 v29, 0xbfb8aa3b, v126
	v_add_f32_e32 v32, 1.0, v27
	v_add_f32_e32 v30, -1.0, v32
	v_sub_f32_e32 v31, v30, v32
	v_add_f32_e32 v31, 1.0, v31
	v_sub_f32_e32 v30, v27, v30
	v_add_f32_e32 v33, v30, v31
	v_frexp_mant_f32_e32 v34, v32
	v_cvt_f64_f32_e32 v[30:31], v32
	v_frexp_exp_i32_f64_e32 v30, v[30:31]
	v_cmp_gt_f32_e32 vcc, s3, v34
	s_mov_b32 s3, 0x3f317218
	v_exp_f32_e32 v29, v29
	v_subbrev_co_u32_e32 v30, vcc, 0, v30, vcc
	v_sub_u32_e32 v31, 0, v30
	v_ldexp_f32 v32, v32, v31
	v_ldexp_f32 v31, v33, v31
	v_add_f32_e32 v33, -1.0, v32
	v_add_f32_e32 v36, 1.0, v32
	v_add_f32_e32 v34, 1.0, v33
	v_add_f32_e32 v37, -1.0, v36
	v_sub_f32_e32 v34, v32, v34
	v_sub_f32_e32 v32, v32, v37
	v_add_f32_e32 v34, v31, v34
	v_add_f32_e32 v31, v31, v32
	v_add_f32_e32 v32, v36, v31
	v_rcp_f32_e32 v37, v32
	v_add_f32_e32 v35, v33, v34
	v_sub_f32_e32 v33, v35, v33
	v_sub_f32_e32 v33, v34, v33
	v_sub_f32_e32 v34, v32, v36
	v_sub_f32_e32 v31, v31, v34
	v_mul_f32_e32 v34, v35, v37
	v_mul_f32_e32 v36, v32, v34
	v_fma_f32 v38, v34, v32, -v36
	v_fmac_f32_e32 v38, v34, v31
	v_add_f32_e32 v39, v36, v38
	v_sub_f32_e32 v40, v35, v39
	v_sub_f32_e32 v35, v35, v40
	v_sub_f32_e32 v36, v39, v36
	v_sub_f32_e32 v35, v35, v39
	v_add_f32_e32 v33, v33, v35
	v_sub_f32_e32 v35, v36, v38
	v_add_f32_e32 v33, v35, v33
	v_add_f32_e32 v35, v40, v33
	v_mul_f32_e32 v36, v37, v35
	v_mul_f32_e32 v38, v32, v36
	v_fma_f32 v32, v36, v32, -v38
	v_fmac_f32_e32 v32, v36, v31
	v_sub_f32_e32 v31, v40, v35
	v_add_f32_e32 v31, v33, v31
	v_add_f32_e32 v33, v38, v32
	v_sub_f32_e32 v39, v35, v33
	v_sub_f32_e32 v35, v35, v39
	v_sub_f32_e32 v38, v33, v38
	v_sub_f32_e32 v33, v35, v33
	v_add_f32_e32 v31, v31, v33
	v_sub_f32_e32 v32, v38, v32
	v_cvt_f32_i32_e32 v30, v30
	v_add_f32_e32 v31, v32, v31
	v_add_f32_e32 v32, v34, v36
	v_add_f32_e32 v31, v39, v31
	v_sub_f32_e32 v33, v32, v34
	v_mul_f32_e32 v31, v37, v31
	v_sub_f32_e32 v33, v36, v33
	v_add_f32_e32 v31, v33, v31
	v_mul_f32_e32 v36, 0x3f317218, v30
	v_add_f32_e32 v33, v32, v31
	v_fma_f32 v37, v30, s3, -v36
	v_mul_f32_e32 v34, v33, v33
	v_fmac_f32_e32 v37, 0xb102e308, v30
	v_sub_f32_e32 v30, v33, v32
	v_fmamk_f32 v35, v34, 0x3e9b6dac, v118
	v_sub_f32_e32 v30, v31, v30
	v_add_f32_e32 v31, v36, v37
	v_fmaak_f32 v35, v34, v35, 0x3f2aaada
	v_sub_f32_e32 v32, v31, v36
	v_ldexp_f32 v36, v33, 1
	v_mul_f32_e32 v33, v33, v34
	v_mul_f32_e32 v33, v33, v35
	v_add_f32_e32 v34, v36, v33
	v_sub_f32_e32 v35, v34, v36
	v_ldexp_f32 v30, v30, 1
	v_sub_f32_e32 v33, v33, v35
	v_add_f32_e32 v30, v30, v33
	v_add_f32_e32 v33, v34, v30
	v_sub_f32_e32 v34, v33, v34
	v_sub_f32_e32 v30, v30, v34
	v_add_f32_e32 v34, v31, v33
	v_sub_f32_e32 v35, v34, v31
	v_sub_f32_e32 v36, v34, v35
	v_sub_f32_e32 v32, v37, v32
	v_sub_f32_e32 v31, v31, v36
	v_sub_f32_e32 v33, v33, v35
	v_add_f32_e32 v31, v33, v31
	v_add_f32_e32 v33, v32, v30
	v_sub_f32_e32 v35, v33, v32
	v_sub_f32_e32 v36, v33, v35
	v_sub_f32_e32 v32, v32, v36
	v_sub_f32_e32 v30, v30, v35
	v_add_f32_e32 v31, v33, v31
	v_add_f32_e32 v30, v30, v32
	v_add_f32_e32 v32, v34, v31
	v_sub_f32_e32 v33, v32, v34
	v_sub_f32_e32 v31, v31, v33
	v_add_f32_e32 v30, v30, v31
	s_mov_b32 s3, 0x7f800000
	v_add_f32_e32 v30, v32, v30
	v_cmp_neq_f32_e32 vcc, s3, v27
	s_mov_b32 s3, 0x33800000
	v_and_b32_e32 v31, 64, v122
	v_cndmask_b32_e32 v30, v119, v30, vcc
	v_cmp_ngt_f32_e32 vcc, -1.0, v27
	v_add_f32_e32 v29, 1.0, v29
	v_rcp_f32_e32 v29, v29
	v_cndmask_b32_e32 v30, v120, v30, vcc
	v_cmp_neq_f32_e32 vcc, -1.0, v27
	s_nop 1
	v_cndmask_b32_e32 v30, v121, v30, vcc
	v_cmp_lt_f32_e64 vcc, |v27|, s3
	s_nop 1
	v_cndmask_b32_e32 v27, v30, v27, vcc
	v_add_u32_e32 v30, -1, v122
	v_cmp_lt_i32_e32 vcc, v30, v31
	v_add_f32_e32 v25, v25, v27
	v_mul_f32_e64 v27, v25, -v125
	v_cndmask_b32_e32 v30, v30, v122, vcc
	v_lshlrev_b32_e32 v30, 2, v30
	ds_bpermute_b32 v30, v30, v27
	v_cmp_eq_u32_e32 vcc, 0, v95
	s_waitcnt lgkmcnt(0)
	v_fma_f32 v25, v25, -v125, v30
	v_cndmask_b32_e32 v25, v25, v27, vcc
	v_add_u32_e32 v27, -2, v122
	v_cmp_lt_i32_e32 vcc, v27, v31
	v_lshl_add_u32 v30, v112, 2, 0
	v_add_u32_e32 v32, 0x21900, v30
	v_cndmask_b32_e32 v27, v27, v122, vcc
	v_lshlrev_b32_e32 v27, 2, v27
	ds_bpermute_b32 v27, v27, v25
	v_cmp_gt_u32_e32 vcc, 2, v95
	ds_write_b32 v32, v29
	v_add_u32_e32 v29, 0x21800, v30
	s_waitcnt lgkmcnt(1)
	v_add_f32_e32 v27, v25, v27
	v_cndmask_b32_e32 v25, v27, v25, vcc
	v_and_or_b32 v27, v112, 56, v31
	v_lshlrev_b32_e32 v27, 2, v27
	ds_bpermute_b32 v33, v27, v25 offset:12
	v_and_b32_e32 v34, 4, v112
	v_cmp_ne_u32_e32 vcc, 0, v34
	s_waitcnt lgkmcnt(0)
	v_add_f32_e32 v33, v25, v33
	v_cndmask_b32_e32 v25, v25, v33, vcc
	ds_bpermute_b32 v27, v27, v25 offset:28
	ds_write_b32 v29, v25
	v_mul_f32_e32 v29, 0x3fb8aa3b, v25
	v_exp_f32_e32 v29, v29
	s_waitcnt lgkmcnt(1)
	v_sub_f32_e32 v25, v27, v25
	v_mul_f32_e32 v25, 0x3fb8aa3b, v25
	v_exp_f32_e32 v25, v25
	v_add_u32_e32 v27, 0x21a00, v30
	ds_write_b32 v27, v29
	v_add_u32_e32 v27, 0x21b00, v30
	ds_write_b32 v27, v25

.Lgdn_done:
	s_cmp_lg_u32 s17, 31
	s_cbranch_scc0 .Lgch_skip
	v_readfirstlane_b32 s0, v180
	s_nop 1
	s_cmpk_lt_u32 s0, 64
	s_cbranch_scc0 .Lgch_skip
	s_lshl_b32 s3, s17, 2
	s_add_u32 s3, s3, 4
.Lgch_poll:
	ds_read_b32 v25, v236 offset:28
	s_waitcnt lgkmcnt(0)
	v_readfirstlane_b32 s1, v25
	s_cmp_ge_u32 s1, s3
	s_cbranch_scc1 .Lgch_go
	s_sleep 1
	s_branch .Lgch_poll
.Lgch_go:
	v_and_b32_e32 v95, 3, v112
	s_waitcnt vmcnt(0)
	v_add_f32_e32 v25, v124, v127
	s_mov_b32 s3, 0xbfb8aa3b
	v_mul_f32_e64 v27, |v25|, s3
	v_exp_f32_e32 v27, v27
	s_mov_b32 s3, 0x3f2aaaab
	v_max_f32_e32 v25, 0, v25
	v_mul_f32_e32 v29, 0xbfb8aa3b, v126
	v_add_f32_e32 v32, 1.0, v27
	v_add_f32_e32 v30, -1.0, v32
	v_sub_f32_e32 v31, v30, v32
	v_add_f32_e32 v31, 1.0, v31
	v_sub_f32_e32 v30, v27, v30
	v_add_f32_e32 v33, v30, v31
	v_frexp_mant_f32_e32 v34, v32
	v_cvt_f64_f32_e32 v[30:31], v32
	v_frexp_exp_i32_f64_e32 v30, v[30:31]
	v_cmp_gt_f32_e32 vcc, s3, v34
	s_mov_b32 s3, 0x3f317218
	v_exp_f32_e32 v29, v29
	v_subbrev_co_u32_e32 v30, vcc, 0, v30, vcc
	v_sub_u32_e32 v31, 0, v30
	v_ldexp_f32 v32, v32, v31
	v_ldexp_f32 v31, v33, v31
	v_add_f32_e32 v33, -1.0, v32
	v_add_f32_e32 v36, 1.0, v32
	v_add_f32_e32 v34, 1.0, v33
	v_add_f32_e32 v37, -1.0, v36
	v_sub_f32_e32 v34, v32, v34
	v_sub_f32_e32 v32, v32, v37
	v_add_f32_e32 v34, v31, v34
	v_add_f32_e32 v31, v31, v32
	v_add_f32_e32 v32, v36, v31
	v_rcp_f32_e32 v37, v32
	v_add_f32_e32 v35, v33, v34
	v_sub_f32_e32 v33, v35, v33
	v_sub_f32_e32 v33, v34, v33
	v_sub_f32_e32 v34, v32, v36
	v_sub_f32_e32 v31, v31, v34
	v_mul_f32_e32 v34, v35, v37
	v_mul_f32_e32 v36, v32, v34
	v_fma_f32 v38, v34, v32, -v36
	v_fmac_f32_e32 v38, v34, v31
	v_add_f32_e32 v39, v36, v38
	v_sub_f32_e32 v40, v35, v39
	v_sub_f32_e32 v35, v35, v40
	v_sub_f32_e32 v36, v39, v36
	v_sub_f32_e32 v35, v35, v39
	v_add_f32_e32 v33, v33, v35
	v_sub_f32_e32 v35, v36, v38
	v_add_f32_e32 v33, v35, v33
	v_add_f32_e32 v35, v40, v33
	v_mul_f32_e32 v36, v37, v35
	v_mul_f32_e32 v38, v32, v36
	v_fma_f32 v32, v36, v32, -v38
	v_fmac_f32_e32 v32, v36, v31
	v_sub_f32_e32 v31, v40, v35
	v_add_f32_e32 v31, v33, v31
	v_add_f32_e32 v33, v38, v32
	v_sub_f32_e32 v39, v35, v33
	v_sub_f32_e32 v35, v35, v39
	v_sub_f32_e32 v38, v33, v38
	v_sub_f32_e32 v33, v35, v33
	v_add_f32_e32 v31, v31, v33
	v_sub_f32_e32 v32, v38, v32
	v_cvt_f32_i32_e32 v30, v30
	v_add_f32_e32 v31, v32, v31
	v_add_f32_e32 v32, v34, v36
	v_add_f32_e32 v31, v39, v31
	v_sub_f32_e32 v33, v32, v34
	v_mul_f32_e32 v31, v37, v31
	v_sub_f32_e32 v33, v36, v33
	v_add_f32_e32 v31, v33, v31
	v_mul_f32_e32 v36, 0x3f317218, v30
	v_add_f32_e32 v33, v32, v31
	v_fma_f32 v37, v30, s3, -v36
	v_mul_f32_e32 v34, v33, v33
	v_fmac_f32_e32 v37, 0xb102e308, v30
	v_sub_f32_e32 v30, v33, v32
	v_fmamk_f32 v35, v34, 0x3e9b6dac, v118
	v_sub_f32_e32 v30, v31, v30
	v_add_f32_e32 v31, v36, v37
	v_fmaak_f32 v35, v34, v35, 0x3f2aaada
	v_sub_f32_e32 v32, v31, v36
	v_ldexp_f32 v36, v33, 1
	v_mul_f32_e32 v33, v33, v34
	v_mul_f32_e32 v33, v33, v35
	v_add_f32_e32 v34, v36, v33
	v_sub_f32_e32 v35, v34, v36
	v_ldexp_f32 v30, v30, 1
	v_sub_f32_e32 v33, v33, v35
	v_add_f32_e32 v30, v30, v33
	v_add_f32_e32 v33, v34, v30
	v_sub_f32_e32 v34, v33, v34
	v_sub_f32_e32 v30, v30, v34
	v_add_f32_e32 v34, v31, v33
	v_sub_f32_e32 v35, v34, v31
	v_sub_f32_e32 v36, v34, v35
	v_sub_f32_e32 v32, v37, v32
	v_sub_f32_e32 v31, v31, v36
	v_sub_f32_e32 v33, v33, v35
	v_add_f32_e32 v31, v33, v31
	v_add_f32_e32 v33, v32, v30
	v_sub_f32_e32 v35, v33, v32
	v_sub_f32_e32 v36, v33, v35
	v_sub_f32_e32 v32, v32, v36
	v_sub_f32_e32 v30, v30, v35
	v_add_f32_e32 v31, v33, v31
	v_add_f32_e32 v30, v30, v32
	v_add_f32_e32 v32, v34, v31
	v_sub_f32_e32 v33, v32, v34
	v_sub_f32_e32 v31, v31, v33
	v_add_f32_e32 v30, v30, v31
	s_mov_b32 s3, 0x7f800000
	v_add_f32_e32 v30, v32, v30
	v_cmp_neq_f32_e32 vcc, s3, v27
	s_mov_b32 s3, 0x33800000
	v_and_b32_e32 v31, 64, v122
	v_cndmask_b32_e32 v30, v119, v30, vcc
	v_cmp_ngt_f32_e32 vcc, -1.0, v27
	v_add_f32_e32 v29, 1.0, v29
	v_rcp_f32_e32 v29, v29
	v_cndmask_b32_e32 v30, v120, v30, vcc
	v_cmp_neq_f32_e32 vcc, -1.0, v27
	s_nop 1
	v_cndmask_b32_e32 v30, v121, v30, vcc
	v_cmp_lt_f32_e64 vcc, |v27|, s3
	s_nop 1
	v_cndmask_b32_e32 v27, v30, v27, vcc
	v_add_u32_e32 v30, -1, v122
	v_cmp_lt_i32_e32 vcc, v30, v31
	v_add_f32_e32 v25, v25, v27
	v_mul_f32_e64 v27, v25, -v125
	v_cndmask_b32_e32 v30, v30, v122, vcc
	v_lshlrev_b32_e32 v30, 2, v30
	ds_bpermute_b32 v30, v30, v27
	v_cmp_eq_u32_e32 vcc, 0, v95
	s_waitcnt lgkmcnt(0)
	v_fma_f32 v25, v25, -v125, v30
	v_cndmask_b32_e32 v25, v25, v27, vcc
	v_add_u32_e32 v27, -2, v122
	v_cmp_lt_i32_e32 vcc, v27, v31
	v_lshl_add_u32 v30, v112, 2, 0
	v_add_u32_e32 v32, 0x21900, v30
	v_cndmask_b32_e32 v27, v27, v122, vcc
	v_lshlrev_b32_e32 v27, 2, v27
	ds_bpermute_b32 v27, v27, v25
	v_cmp_gt_u32_e32 vcc, 2, v95
	ds_write_b32 v32, v29
	v_add_u32_e32 v29, 0x21800, v30
	s_waitcnt lgkmcnt(1)
	v_add_f32_e32 v27, v25, v27
	v_cndmask_b32_e32 v25, v27, v25, vcc
	v_and_or_b32 v27, v112, 56, v31
	v_lshlrev_b32_e32 v27, 2, v27
	ds_bpermute_b32 v33, v27, v25 offset:12
	v_and_b32_e32 v34, 4, v112
	v_cmp_ne_u32_e32 vcc, 0, v34
	s_waitcnt lgkmcnt(0)
	v_add_f32_e32 v33, v25, v33
	v_cndmask_b32_e32 v25, v25, v33, vcc
	ds_bpermute_b32 v27, v27, v25 offset:28
	ds_write_b32 v29, v25
	v_mul_f32_e32 v29, 0x3fb8aa3b, v25
	v_exp_f32_e32 v29, v29
	s_waitcnt lgkmcnt(1)
	v_sub_f32_e32 v25, v27, v25
	v_mul_f32_e32 v25, 0x3fb8aa3b, v25
	v_exp_f32_e32 v25, v25
	v_add_u32_e32 v27, 0x21a00, v30
	ds_write_b32 v27, v29
	v_add_u32_e32 v27, 0x21b00, v30
	ds_write_b32 v27, v25
